# v23: MLP-in epilogue without the 128 redundant canonicalising v_max (relu v_max canonicalises); pk->use and store-data spacing kept
# speedup vs baseline: 1.0067x; 1.0042x over previous
.LBB0_104:
	v_lshl_add_u32 v142, s43, 8, v146
	v_lshl_or_b32 v140, s42, 8, v148
	v_ashrrev_i32_e32 v143, 31, v142
	v_readlane_b32 s14, v255, 11
	v_ashrrev_i32_e32 v141, 31, v140
	v_lshlrev_b64 v[144:145], 14, v[142:143]
	v_readlane_b32 s15, v255, 12
	v_lshl_add_u64 v[150:151], s[14:15], 0, v[144:145]
	v_lshlrev_b64 v[144:145], 1, v[140:141]
	v_max_f32_e32 v125, 0, v125
	v_max_f32_e32 v124, 0, v124
	v_max_f32_e32 v127, 0, v127
	v_max_f32_e32 v126, 0, v126
	v_max_f32_e32 v121, 0, v121
	v_max_f32_e32 v120, 0, v120
	v_max_f32_e32 v123, 0, v123
	v_max_f32_e32 v122, 0, v122
	v_lshl_add_u64 v[140:141], v[150:151], 0, v[144:145]
	v_pk_mul_f32 v[126:127], v[126:127], v[126:127]
	v_pk_mul_f32 v[124:125], v[124:125], v[124:125]
	v_pk_mul_f32 v[150:151], v[122:123], v[122:123]
	v_pk_mul_f32 v[122:123], v[120:121], v[120:121]
	v_cvt_pk_bf16_f32 v120, v124, v125
	v_cvt_pk_bf16_f32 v121, v126, v127
	v_max_f32_e32 v117, 0, v117
	v_max_f32_e32 v116, 0, v116
	v_max_f32_e32 v113, 0, v113
	v_max_f32_e32 v112, 0, v112
	v_max_f32_e32 v115, 0, v115
	v_max_f32_e32 v114, 0, v114
	v_cvt_pk_bf16_f32 v122, v122, v123
	v_cvt_pk_bf16_f32 v123, v150, v151
	global_store_dwordx4 v[140:141], v[120:123], off
	v_max_f32_e32 v119, 0, v119
	v_max_f32_e32 v118, 0, v118
	v_pk_mul_f32 v[116:117], v[116:117], v[116:117]
	v_pk_mul_f32 v[120:121], v[114:115], v[114:115]
	v_pk_mul_f32 v[114:115], v[112:113], v[112:113]
	v_cvt_pk_bf16_f32 v112, v116, v117
	v_pk_mul_f32 v[118:119], v[118:119], v[118:119]
	s_nop 0
	v_cvt_pk_bf16_f32 v113, v118, v119
	v_cvt_pk_bf16_f32 v114, v114, v115
	v_cvt_pk_bf16_f32 v115, v120, v121
	global_store_dwordx4 v[140:141], v[112:115], off offset:256
	s_nop 1
	v_or_b32_e32 v112, 16, v142
	v_ashrrev_i32_e32 v113, 31, v112
	v_lshlrev_b64 v[112:113], 14, v[112:113]
	v_lshl_add_u64 v[112:113], s[14:15], 0, v[112:113]
	v_max_f32_e32 v109, 0, v109
	v_max_f32_e32 v108, 0, v108
	v_max_f32_e32 v111, 0, v111
	v_max_f32_e32 v110, 0, v110
	v_max_f32_e32 v105, 0, v105
	v_max_f32_e32 v104, 0, v104
	v_max_f32_e32 v107, 0, v107
	v_max_f32_e32 v106, 0, v106
	v_lshl_add_u64 v[112:113], v[112:113], 0, v[144:145]
	v_pk_mul_f32 v[110:111], v[110:111], v[110:111]
	v_pk_mul_f32 v[108:109], v[108:109], v[108:109]
	v_pk_mul_f32 v[114:115], v[106:107], v[106:107]
	v_pk_mul_f32 v[106:107], v[104:105], v[104:105]
	v_cvt_pk_bf16_f32 v104, v108, v109
	v_cvt_pk_bf16_f32 v105, v110, v111
	v_max_f32_e32 v101, 0, v101
	v_max_f32_e32 v100, 0, v100
	v_max_f32_e32 v97, 0, v97
	v_max_f32_e32 v96, 0, v96
	v_max_f32_e32 v99, 0, v99
	v_max_f32_e32 v98, 0, v98
	v_cvt_pk_bf16_f32 v106, v106, v107
	v_cvt_pk_bf16_f32 v107, v114, v115
	global_store_dwordx4 v[112:113], v[104:107], off
	v_max_f32_e32 v103, 0, v103
	v_max_f32_e32 v102, 0, v102
	v_pk_mul_f32 v[100:101], v[100:101], v[100:101]
	v_pk_mul_f32 v[104:105], v[98:99], v[98:99]
	v_pk_mul_f32 v[98:99], v[96:97], v[96:97]
	v_cvt_pk_bf16_f32 v96, v100, v101
	v_pk_mul_f32 v[102:103], v[102:103], v[102:103]
	s_nop 0
	v_cvt_pk_bf16_f32 v97, v102, v103
	v_cvt_pk_bf16_f32 v98, v98, v99
	v_cvt_pk_bf16_f32 v99, v104, v105
	global_store_dwordx4 v[112:113], v[96:99], off offset:256
	s_nop 1
	v_or_b32_e32 v96, 32, v142
	v_ashrrev_i32_e32 v97, 31, v96
	v_lshlrev_b64 v[96:97], 14, v[96:97]
	v_lshl_add_u64 v[96:97], s[14:15], 0, v[96:97]
	v_max_f32_e32 v93, 0, v93
	v_max_f32_e32 v92, 0, v92
	v_max_f32_e32 v95, 0, v95
	v_max_f32_e32 v94, 0, v94
	v_max_f32_e32 v89, 0, v89
	v_max_f32_e32 v88, 0, v88
	v_max_f32_e32 v91, 0, v91
	v_max_f32_e32 v90, 0, v90
	v_lshl_add_u64 v[96:97], v[96:97], 0, v[144:145]
	v_pk_mul_f32 v[94:95], v[94:95], v[94:95]
	v_pk_mul_f32 v[92:93], v[92:93], v[92:93]
	v_pk_mul_f32 v[98:99], v[90:91], v[90:91]
	v_pk_mul_f32 v[90:91], v[88:89], v[88:89]
	v_cvt_pk_bf16_f32 v88, v92, v93
	v_cvt_pk_bf16_f32 v89, v94, v95
	v_max_f32_e32 v85, 0, v85
	v_max_f32_e32 v84, 0, v84
	v_max_f32_e32 v81, 0, v81
	v_max_f32_e32 v80, 0, v80
	v_max_f32_e32 v83, 0, v83
	v_max_f32_e32 v82, 0, v82
	v_cvt_pk_bf16_f32 v90, v90, v91
	v_cvt_pk_bf16_f32 v91, v98, v99
	global_store_dwordx4 v[96:97], v[88:91], off
	v_max_f32_e32 v87, 0, v87
	v_max_f32_e32 v86, 0, v86
	v_pk_mul_f32 v[84:85], v[84:85], v[84:85]
	v_pk_mul_f32 v[88:89], v[82:83], v[82:83]
	v_pk_mul_f32 v[82:83], v[80:81], v[80:81]
	v_cvt_pk_bf16_f32 v80, v84, v85
	v_pk_mul_f32 v[86:87], v[86:87], v[86:87]
	s_nop 0
	v_cvt_pk_bf16_f32 v81, v86, v87
	v_cvt_pk_bf16_f32 v82, v82, v83
	v_cvt_pk_bf16_f32 v83, v88, v89
	global_store_dwordx4 v[96:97], v[80:83], off offset:256
	s_nop 1
	v_or_b32_e32 v80, 48, v142
	v_ashrrev_i32_e32 v81, 31, v80
	v_lshlrev_b64 v[80:81], 14, v[80:81]
	v_lshl_add_u64 v[80:81], s[14:15], 0, v[80:81]
	v_max_f32_e32 v77, 0, v77
	v_max_f32_e32 v76, 0, v76
	v_max_f32_e32 v79, 0, v79
	v_max_f32_e32 v78, 0, v78
	v_max_f32_e32 v73, 0, v73
	v_max_f32_e32 v72, 0, v72
	v_max_f32_e32 v75, 0, v75
	v_max_f32_e32 v74, 0, v74
	v_lshl_add_u64 v[80:81], v[80:81], 0, v[144:145]
	v_pk_mul_f32 v[78:79], v[78:79], v[78:79]
	v_pk_mul_f32 v[76:77], v[76:77], v[76:77]
	v_pk_mul_f32 v[82:83], v[74:75], v[74:75]
	v_pk_mul_f32 v[74:75], v[72:73], v[72:73]
	v_cvt_pk_bf16_f32 v72, v76, v77
	v_cvt_pk_bf16_f32 v73, v78, v79
	v_max_f32_e32 v65, 0, v65
	v_max_f32_e32 v64, 0, v64
	v_max_f32_e32 v67, 0, v67
	v_max_f32_e32 v66, 0, v66
	v_cvt_pk_bf16_f32 v74, v74, v75
	v_cvt_pk_bf16_f32 v75, v82, v83
	global_store_dwordx4 v[80:81], v[72:75], off
	v_max_f32_e32 v69, 0, v69
	v_max_f32_e32 v68, 0, v68
	v_max_f32_e32 v71, 0, v71
	v_max_f32_e32 v70, 0, v70
	v_pk_mul_f32 v[72:73], v[66:67], v[66:67]
	v_pk_mul_f32 v[66:67], v[64:65], v[64:65]
	v_max_f32_e32 v61, 0, v61
	v_max_f32_e32 v60, 0, v60
	v_pk_mul_f32 v[70:71], v[70:71], v[70:71]
	v_pk_mul_f32 v[68:69], v[68:69], v[68:69]
	s_nop 0
	v_cvt_pk_bf16_f32 v64, v68, v69
	v_cvt_pk_bf16_f32 v65, v70, v71
	v_cvt_pk_bf16_f32 v66, v66, v67
	v_cvt_pk_bf16_f32 v67, v72, v73
	v_max_f32_e32 v57, 0, v57
	v_max_f32_e32 v56, 0, v56
	v_max_f32_e32 v59, 0, v59
	v_max_f32_e32 v58, 0, v58
	v_pk_mul_f32 v[60:61], v[60:61], v[60:61]
	s_mov_b32 s9, 0x200000
	global_store_dwordx4 v[80:81], v[64:67], off offset:256
	v_max_f32_e32 v63, 0, v63
	v_max_f32_e32 v62, 0, v62
	v_pk_mul_f32 v[66:67], v[58:59], v[58:59]
	v_pk_mul_f32 v[58:59], v[56:57], v[56:57]
	v_cvt_pk_bf16_f32 v56, v60, v61
	v_add_co_u32_e32 v60, vcc, s9, v140
	v_pk_mul_f32 v[62:63], v[62:63], v[62:63]
	v_addc_co_u32_e32 v61, vcc, 0, v141, vcc
	v_cvt_pk_bf16_f32 v57, v62, v63
	v_max_f32_e32 v49, 0, v49
	v_max_f32_e32 v48, 0, v48
	v_max_f32_e32 v51, 0, v51
	v_max_f32_e32 v50, 0, v50
	s_mov_b64 s[14:15], 0x200000
	v_cvt_pk_bf16_f32 v58, v58, v59
	v_cvt_pk_bf16_f32 v59, v66, v67
	global_store_dwordx4 v[60:61], v[56:59], off
	v_max_f32_e32 v53, 0, v53
	v_max_f32_e32 v52, 0, v52
	v_max_f32_e32 v55, 0, v55
	v_max_f32_e32 v54, 0, v54
	v_pk_mul_f32 v[56:57], v[50:51], v[50:51]
	v_pk_mul_f32 v[50:51], v[48:49], v[48:49]
	v_max_f32_e32 v45, 0, v45
	v_max_f32_e32 v44, 0, v44
	v_lshl_add_u64 v[64:65], v[140:141], 0, s[14:15]
	v_pk_mul_f32 v[54:55], v[54:55], v[54:55]
	v_pk_mul_f32 v[52:53], v[52:53], v[52:53]
	s_nop 0
	v_cvt_pk_bf16_f32 v48, v52, v53
	v_cvt_pk_bf16_f32 v49, v54, v55
	v_cvt_pk_bf16_f32 v50, v50, v51
	v_cvt_pk_bf16_f32 v51, v56, v57
	v_max_f32_e32 v41, 0, v41
	v_max_f32_e32 v40, 0, v40
	v_max_f32_e32 v43, 0, v43
	v_max_f32_e32 v42, 0, v42
	v_pk_mul_f32 v[44:45], v[44:45], v[44:45]
	s_mov_b32 s9, 0x240000
	global_store_dwordx4 v[64:65], v[48:51], off offset:256
	v_max_f32_e32 v47, 0, v47
	v_max_f32_e32 v46, 0, v46
	v_pk_mul_f32 v[50:51], v[42:43], v[42:43]
	v_pk_mul_f32 v[42:43], v[40:41], v[40:41]
	v_cvt_pk_bf16_f32 v40, v44, v45
	v_add_co_u32_e32 v44, vcc, s9, v140
	v_pk_mul_f32 v[46:47], v[46:47], v[46:47]
	v_addc_co_u32_e32 v45, vcc, 0, v141, vcc
	v_cvt_pk_bf16_f32 v41, v46, v47
	v_max_f32_e32 v33, 0, v33
	v_max_f32_e32 v32, 0, v32
	v_max_f32_e32 v35, 0, v35
	v_max_f32_e32 v34, 0, v34
	s_mov_b64 s[14:15], 0x240000
	v_cvt_pk_bf16_f32 v42, v42, v43
	v_cvt_pk_bf16_f32 v43, v50, v51
	global_store_dwordx4 v[44:45], v[40:43], off
	v_max_f32_e32 v37, 0, v37
	v_max_f32_e32 v36, 0, v36
	v_max_f32_e32 v39, 0, v39
	v_max_f32_e32 v38, 0, v38
	v_pk_mul_f32 v[40:41], v[34:35], v[34:35]
	v_pk_mul_f32 v[34:35], v[32:33], v[32:33]
	v_max_f32_e32 v29, 0, v29
	v_max_f32_e32 v28, 0, v28
	v_lshl_add_u64 v[48:49], v[140:141], 0, s[14:15]
	v_pk_mul_f32 v[38:39], v[38:39], v[38:39]
	v_pk_mul_f32 v[36:37], v[36:37], v[36:37]
	s_nop 0
	v_cvt_pk_bf16_f32 v32, v36, v37
	v_cvt_pk_bf16_f32 v33, v38, v39
	v_cvt_pk_bf16_f32 v34, v34, v35
	v_cvt_pk_bf16_f32 v35, v40, v41
	v_max_f32_e32 v25, 0, v25
	v_max_f32_e32 v24, 0, v24
	v_max_f32_e32 v27, 0, v27
	v_max_f32_e32 v26, 0, v26
	v_pk_mul_f32 v[28:29], v[28:29], v[28:29]
	s_mov_b32 s9, 0x280000
	global_store_dwordx4 v[48:49], v[32:35], off offset:256
	v_max_f32_e32 v31, 0, v31
	v_max_f32_e32 v30, 0, v30
	v_pk_mul_f32 v[34:35], v[26:27], v[26:27]
	v_pk_mul_f32 v[26:27], v[24:25], v[24:25]
	v_cvt_pk_bf16_f32 v24, v28, v29
	v_add_co_u32_e32 v28, vcc, s9, v140
	v_pk_mul_f32 v[30:31], v[30:31], v[30:31]
	v_addc_co_u32_e32 v29, vcc, 0, v141, vcc
	v_cvt_pk_bf16_f32 v25, v30, v31
	v_max_f32_e32 v17, 0, v17
	v_max_f32_e32 v16, 0, v16
	v_max_f32_e32 v19, 0, v19
	v_max_f32_e32 v18, 0, v18
	s_mov_b64 s[14:15], 0x280000
	v_cvt_pk_bf16_f32 v26, v26, v27
	v_cvt_pk_bf16_f32 v27, v34, v35
	global_store_dwordx4 v[28:29], v[24:27], off
	v_max_f32_e32 v21, 0, v21
	v_max_f32_e32 v20, 0, v20
	v_max_f32_e32 v23, 0, v23
	v_max_f32_e32 v22, 0, v22
	v_pk_mul_f32 v[24:25], v[18:19], v[18:19]
	v_pk_mul_f32 v[18:19], v[16:17], v[16:17]
	v_max_f32_e32 v13, 0, v13
	v_max_f32_e32 v12, 0, v12
	v_lshl_add_u64 v[32:33], v[140:141], 0, s[14:15]
	v_pk_mul_f32 v[22:23], v[22:23], v[22:23]
	v_pk_mul_f32 v[20:21], v[20:21], v[20:21]
	s_nop 0
	v_cvt_pk_bf16_f32 v16, v20, v21
	v_cvt_pk_bf16_f32 v17, v22, v23
	v_cvt_pk_bf16_f32 v18, v18, v19
	v_cvt_pk_bf16_f32 v19, v24, v25
	v_max_f32_e32 v9, 0, v9
	v_max_f32_e32 v8, 0, v8
	v_max_f32_e32 v11, 0, v11
	v_max_f32_e32 v10, 0, v10
	v_pk_mul_f32 v[12:13], v[12:13], v[12:13]
	s_mov_b32 s9, 0x2c0000
	global_store_dwordx4 v[32:33], v[16:19], off offset:256
	v_max_f32_e32 v15, 0, v15
	v_max_f32_e32 v14, 0, v14
	v_pk_mul_f32 v[18:19], v[10:11], v[10:11]
	v_pk_mul_f32 v[10:11], v[8:9], v[8:9]
	v_cvt_pk_bf16_f32 v8, v12, v13
	v_add_co_u32_e32 v12, vcc, s9, v140
	s_mov_b64 s[14:15], 0x2c0000
	v_pk_mul_f32 v[14:15], v[14:15], v[14:15]
	v_addc_co_u32_e32 v13, vcc, 0, v141, vcc
	v_cvt_pk_bf16_f32 v9, v14, v15
	v_max_f32_e32 v1, 0, v1
	v_max_f32_e32 v0, 0, v0
	v_max_f32_e32 v3, 0, v3
	v_max_f32_e32 v2, 0, v2
	v_lshl_add_u64 v[16:17], v[140:141], 0, s[14:15]
	v_cvt_pk_bf16_f32 v10, v10, v11
	v_cvt_pk_bf16_f32 v11, v18, v19
	global_store_dwordx4 v[12:13], v[8:11], off
	v_max_f32_e32 v5, 0, v5
	v_max_f32_e32 v4, 0, v4
	v_max_f32_e32 v7, 0, v7
	v_max_f32_e32 v6, 0, v6
	v_pk_mul_f32 v[8:9], v[2:3], v[2:3]
	v_pk_mul_f32 v[2:3], v[0:1], v[0:1]
	s_andn2_b64 vcc, exec, s[38:39]
	s_mov_b64 s[14:15], -1
	v_pk_mul_f32 v[6:7], v[6:7], v[6:7]
	v_pk_mul_f32 v[4:5], v[4:5], v[4:5]
	s_nop 0
	v_cvt_pk_bf16_f32 v0, v4, v5
	v_cvt_pk_bf16_f32 v1, v6, v7
	v_cvt_pk_bf16_f32 v2, v2, v3
	v_cvt_pk_bf16_f32 v3, v8, v9
	global_store_dwordx4 v[16:17], v[0:3], off offset:256
	s_cbranch_vccnz .LBB0_93
	s_andn2_b64 vcc, exec, s[4:5]
	s_cbranch_vccnz .LBB0_92
	s_barrier
	s_branch .LBB0_92
